# stack: epilogue-before-last-barrier on all six GEMMs + in-projection plain stores lane-transposed with SGPR-base addressing + kv conv-item rebalance
# speedup vs baseline: 1.0073x; 1.0073x over previous
.Lepib_inp_exit:
.Lpeelx0:
	s_lshl_b32 s7, s34, 8
	s_cmp_lt_i32 s35, 28
	s_mov_b64 s[4:5], -1
	s_cbranch_scc0 .LBB0_431
	s_add_i32 s16, s7, s27
	v_or_b32_e32 v207, s16, v192
	s_cmp_gt_i32 s35, 3
	s_cbranch_scc0 .LBB0_411
	s_add_i32 s4, s35, -12
	s_cmp_gt_u32 s4, 7
	s_mov_b64 s[4:5], -1
	s_cbranch_scc0 .LBB0_408
	s_waitcnt lgkmcnt(0)
	s_lshl_b32 s4, s35, 8
	s_add_i32 s5, s4, 0xfffffc00
	s_cmp_lt_u32 s35, 12
	s_cselect_b32 s4, s4, s5
	v_and_b32_e32 v11, 8, v220
	v_cmp_ne_u32_e32 vcc, 0, v11
	v_bfe_u32 v10, v220, 3, 3
	v_and_b32_e32 v12, 0x60, v194
	v_lshlrev_b32_e32 v12, 1, v12
	v_and_b32_e32 v13, 7, v220
	v_lshl_or_b32 v12, v13, 3, v12
	v_or_b32_e32 v32, s4, v12
	v_or_b32_e32 v14, s16, v10
	v_mul_lo_u32 v0, v14, s33
	v_lshl_add_u32 v16, v32, 1, v0
	v_and_b32_e32 v13, 4, v220
	v_lshl_or_b32 v13, v13, 1, v10
	v_and_b32_e32 v12, 3, v220
	v_lshl_or_b32 v13, v12, 4, v13
	v_lshlrev_b32_e32 v13, 2, v13
	v_add_u32_e32 v17, 0x30000, v16
	v_add_u32_e32 v18, 0x30000, v17
	v_add_u32_e32 v19, 0x30000, v18
	v_add_u32_e32 v20, 0x180000, v16
	v_add_u32_e32 v21, 0x30000, v20
	v_add_u32_e32 v22, 0x30000, v21
	v_add_u32_e32 v23, 0x30000, v22
	v_cvt_pk_f16_f32 v158, v158, v159
	v_cvt_pk_f16_f32 v159, v160, v161
	v_cvt_pk_f16_f32 v160, v142, v143
	v_cvt_pk_f16_f32 v161, v144, v145
	v_cvt_pk_f16_f32 v94, v94, v95
	v_cvt_pk_f16_f32 v95, v96, v97
	v_cvt_pk_f16_f32 v96, v78, v79
	v_cvt_pk_f16_f32 v97, v80, v81
	v_mov_b32_dpp v0, v158 row_ror:8 row_mask:0xf bank_mask:0xf
	v_mov_b32_dpp v1, v159 row_ror:8 row_mask:0xf bank_mask:0xf
	v_mov_b32_dpp v2, v160 row_ror:8 row_mask:0xf bank_mask:0xf
	v_mov_b32_dpp v3, v161 row_ror:8 row_mask:0xf bank_mask:0xf
	v_mov_b32_dpp v4, v94 row_ror:8 row_mask:0xf bank_mask:0xf
	v_mov_b32_dpp v5, v95 row_ror:8 row_mask:0xf bank_mask:0xf
	v_mov_b32_dpp v6, v96 row_ror:8 row_mask:0xf bank_mask:0xf
	v_mov_b32_dpp v7, v97 row_ror:8 row_mask:0xf bank_mask:0xf
	v_cndmask_b32_e32 v158, v158, v4, vcc
	v_cndmask_b32_e32 v159, v159, v5, vcc
	v_cndmask_b32_e32 v160, v160, v6, vcc
	v_cndmask_b32_e32 v161, v161, v7, vcc
	v_cndmask_b32_e32 v94, v0, v94, vcc
	v_cndmask_b32_e32 v95, v1, v95, vcc
	v_cndmask_b32_e32 v96, v2, v96, vcc
	v_cndmask_b32_e32 v97, v3, v97, vcc
	ds_bpermute_b32 v158, v13, v158
	ds_bpermute_b32 v159, v13, v159
	ds_bpermute_b32 v160, v13, v160
	ds_bpermute_b32 v161, v13, v161
	ds_bpermute_b32 v94, v13, v94
	ds_bpermute_b32 v95, v13, v95
	ds_bpermute_b32 v96, v13, v96
	ds_bpermute_b32 v97, v13, v97
	v_cvt_pk_f16_f32 v150, v150, v151
	v_cvt_pk_f16_f32 v151, v152, v153
	v_cvt_pk_f16_f32 v152, v134, v135
	v_cvt_pk_f16_f32 v153, v136, v137
	v_cvt_pk_f16_f32 v86, v86, v87
	v_cvt_pk_f16_f32 v87, v88, v89
	v_cvt_pk_f16_f32 v88, v70, v71
	v_cvt_pk_f16_f32 v89, v72, v73
	v_mov_b32_dpp v0, v150 row_ror:8 row_mask:0xf bank_mask:0xf
	v_mov_b32_dpp v1, v151 row_ror:8 row_mask:0xf bank_mask:0xf
	v_mov_b32_dpp v2, v152 row_ror:8 row_mask:0xf bank_mask:0xf
	v_mov_b32_dpp v3, v153 row_ror:8 row_mask:0xf bank_mask:0xf
	v_mov_b32_dpp v4, v86 row_ror:8 row_mask:0xf bank_mask:0xf
	v_mov_b32_dpp v5, v87 row_ror:8 row_mask:0xf bank_mask:0xf
	v_mov_b32_dpp v6, v88 row_ror:8 row_mask:0xf bank_mask:0xf
	v_mov_b32_dpp v7, v89 row_ror:8 row_mask:0xf bank_mask:0xf
	v_cndmask_b32_e32 v150, v150, v4, vcc
	v_cndmask_b32_e32 v151, v151, v5, vcc
	v_cndmask_b32_e32 v152, v152, v6, vcc
	v_cndmask_b32_e32 v153, v153, v7, vcc
	v_cndmask_b32_e32 v86, v0, v86, vcc
	v_cndmask_b32_e32 v87, v1, v87, vcc
	v_cndmask_b32_e32 v88, v2, v88, vcc
	v_cndmask_b32_e32 v89, v3, v89, vcc
	ds_bpermute_b32 v150, v13, v150
	ds_bpermute_b32 v151, v13, v151
	ds_bpermute_b32 v152, v13, v152
	ds_bpermute_b32 v153, v13, v153
	ds_bpermute_b32 v86, v13, v86
	ds_bpermute_b32 v87, v13, v87
	ds_bpermute_b32 v88, v13, v88
	ds_bpermute_b32 v89, v13, v89
	s_waitcnt lgkmcnt(8)
	v_add_u32_e32 v10, 0x18000, v16
	global_store_dwordx4 v16, v[158:161], s[70:71]
	global_store_dwordx4 v10, v[94:97], s[70:71]
	v_cvt_pk_f16_f32 v154, v154, v155
	v_cvt_pk_f16_f32 v155, v156, v157
	v_cvt_pk_f16_f32 v156, v138, v139
	v_cvt_pk_f16_f32 v157, v140, v141
	v_cvt_pk_f16_f32 v90, v90, v91
	v_cvt_pk_f16_f32 v91, v92, v93
	v_cvt_pk_f16_f32 v92, v74, v75
	v_cvt_pk_f16_f32 v93, v76, v77
	v_mov_b32_dpp v0, v154 row_ror:8 row_mask:0xf bank_mask:0xf
	v_mov_b32_dpp v1, v155 row_ror:8 row_mask:0xf bank_mask:0xf
	v_mov_b32_dpp v2, v156 row_ror:8 row_mask:0xf bank_mask:0xf
	v_mov_b32_dpp v3, v157 row_ror:8 row_mask:0xf bank_mask:0xf
	v_mov_b32_dpp v4, v90 row_ror:8 row_mask:0xf bank_mask:0xf
	v_mov_b32_dpp v5, v91 row_ror:8 row_mask:0xf bank_mask:0xf
	v_mov_b32_dpp v6, v92 row_ror:8 row_mask:0xf bank_mask:0xf
	v_mov_b32_dpp v7, v93 row_ror:8 row_mask:0xf bank_mask:0xf
	v_cndmask_b32_e32 v154, v154, v4, vcc
	v_cndmask_b32_e32 v155, v155, v5, vcc
	v_cndmask_b32_e32 v156, v156, v6, vcc
	v_cndmask_b32_e32 v157, v157, v7, vcc
	v_cndmask_b32_e32 v90, v0, v90, vcc
	v_cndmask_b32_e32 v91, v1, v91, vcc
	v_cndmask_b32_e32 v92, v2, v92, vcc
	v_cndmask_b32_e32 v93, v3, v93, vcc
	ds_bpermute_b32 v154, v13, v154
	ds_bpermute_b32 v155, v13, v155
	ds_bpermute_b32 v156, v13, v156
	ds_bpermute_b32 v157, v13, v157
	ds_bpermute_b32 v90, v13, v90
	ds_bpermute_b32 v91, v13, v91
	ds_bpermute_b32 v92, v13, v92
	ds_bpermute_b32 v93, v13, v93
	s_waitcnt lgkmcnt(8)
	v_add_u32_e32 v10, 0x18000, v17
	global_store_dwordx4 v17, v[150:153], s[70:71]
	global_store_dwordx4 v10, v[86:89], s[70:71]
	v_cvt_pk_f16_f32 v146, v146, v147
	v_cvt_pk_f16_f32 v147, v148, v149
	v_cvt_pk_f16_f32 v148, v130, v131
	v_cvt_pk_f16_f32 v149, v132, v133
	v_cvt_pk_f16_f32 v82, v82, v83
	v_cvt_pk_f16_f32 v83, v84, v85
	v_cvt_pk_f16_f32 v84, v66, v67
	v_cvt_pk_f16_f32 v85, v68, v69
	v_mov_b32_dpp v0, v146 row_ror:8 row_mask:0xf bank_mask:0xf
	v_mov_b32_dpp v1, v147 row_ror:8 row_mask:0xf bank_mask:0xf
	v_mov_b32_dpp v2, v148 row_ror:8 row_mask:0xf bank_mask:0xf
	v_mov_b32_dpp v3, v149 row_ror:8 row_mask:0xf bank_mask:0xf
	v_mov_b32_dpp v4, v82 row_ror:8 row_mask:0xf bank_mask:0xf
	v_mov_b32_dpp v5, v83 row_ror:8 row_mask:0xf bank_mask:0xf
	v_mov_b32_dpp v6, v84 row_ror:8 row_mask:0xf bank_mask:0xf
	v_mov_b32_dpp v7, v85 row_ror:8 row_mask:0xf bank_mask:0xf
	v_cndmask_b32_e32 v146, v146, v4, vcc
	v_cndmask_b32_e32 v147, v147, v5, vcc
	v_cndmask_b32_e32 v148, v148, v6, vcc
	v_cndmask_b32_e32 v149, v149, v7, vcc
	v_cndmask_b32_e32 v82, v0, v82, vcc
	v_cndmask_b32_e32 v83, v1, v83, vcc
	v_cndmask_b32_e32 v84, v2, v84, vcc
	v_cndmask_b32_e32 v85, v3, v85, vcc
	ds_bpermute_b32 v146, v13, v146
	ds_bpermute_b32 v147, v13, v147
	ds_bpermute_b32 v148, v13, v148
	ds_bpermute_b32 v149, v13, v149
	ds_bpermute_b32 v82, v13, v82
	ds_bpermute_b32 v83, v13, v83
	ds_bpermute_b32 v84, v13, v84
	ds_bpermute_b32 v85, v13, v85
	s_waitcnt lgkmcnt(8)
	v_add_u32_e32 v10, 0x18000, v18
	global_store_dwordx4 v18, v[154:157], s[70:71]
	global_store_dwordx4 v10, v[90:93], s[70:71]
	v_cvt_pk_f16_f32 v126, v126, v127
	v_cvt_pk_f16_f32 v127, v128, v129
	v_cvt_pk_f16_f32 v128, v110, v111
	v_cvt_pk_f16_f32 v129, v112, v113
	v_cvt_pk_f16_f32 v62, v62, v63
	v_cvt_pk_f16_f32 v63, v64, v65
	v_cvt_pk_f16_f32 v64, v46, v47
	v_cvt_pk_f16_f32 v65, v48, v49
	v_mov_b32_dpp v0, v126 row_ror:8 row_mask:0xf bank_mask:0xf
	v_mov_b32_dpp v1, v127 row_ror:8 row_mask:0xf bank_mask:0xf
	v_mov_b32_dpp v2, v128 row_ror:8 row_mask:0xf bank_mask:0xf
	v_mov_b32_dpp v3, v129 row_ror:8 row_mask:0xf bank_mask:0xf
	v_mov_b32_dpp v4, v62 row_ror:8 row_mask:0xf bank_mask:0xf
	v_mov_b32_dpp v5, v63 row_ror:8 row_mask:0xf bank_mask:0xf
	v_mov_b32_dpp v6, v64 row_ror:8 row_mask:0xf bank_mask:0xf
	v_mov_b32_dpp v7, v65 row_ror:8 row_mask:0xf bank_mask:0xf
	v_cndmask_b32_e32 v126, v126, v4, vcc
	v_cndmask_b32_e32 v127, v127, v5, vcc
	v_cndmask_b32_e32 v128, v128, v6, vcc
	v_cndmask_b32_e32 v129, v129, v7, vcc
	v_cndmask_b32_e32 v62, v0, v62, vcc
	v_cndmask_b32_e32 v63, v1, v63, vcc
	v_cndmask_b32_e32 v64, v2, v64, vcc
	v_cndmask_b32_e32 v65, v3, v65, vcc
	ds_bpermute_b32 v126, v13, v126
	ds_bpermute_b32 v127, v13, v127
	ds_bpermute_b32 v128, v13, v128
	ds_bpermute_b32 v129, v13, v129
	ds_bpermute_b32 v62, v13, v62
	ds_bpermute_b32 v63, v13, v63
	ds_bpermute_b32 v64, v13, v64
	ds_bpermute_b32 v65, v13, v65
	s_waitcnt lgkmcnt(8)
	v_add_u32_e32 v10, 0x18000, v19
	global_store_dwordx4 v19, v[146:149], s[70:71]
	global_store_dwordx4 v10, v[82:85], s[70:71]
	v_cvt_pk_f16_f32 v118, v118, v119
	v_cvt_pk_f16_f32 v119, v120, v121
	v_cvt_pk_f16_f32 v120, v102, v103
	v_cvt_pk_f16_f32 v121, v104, v105
	v_cvt_pk_f16_f32 v54, v54, v55
	v_cvt_pk_f16_f32 v55, v56, v57
	v_cvt_pk_f16_f32 v56, v38, v39
	v_cvt_pk_f16_f32 v57, v40, v41
	v_mov_b32_dpp v0, v118 row_ror:8 row_mask:0xf bank_mask:0xf
	v_mov_b32_dpp v1, v119 row_ror:8 row_mask:0xf bank_mask:0xf
	v_mov_b32_dpp v2, v120 row_ror:8 row_mask:0xf bank_mask:0xf
	v_mov_b32_dpp v3, v121 row_ror:8 row_mask:0xf bank_mask:0xf
	v_mov_b32_dpp v4, v54 row_ror:8 row_mask:0xf bank_mask:0xf
	v_mov_b32_dpp v5, v55 row_ror:8 row_mask:0xf bank_mask:0xf
	v_mov_b32_dpp v6, v56 row_ror:8 row_mask:0xf bank_mask:0xf
	v_mov_b32_dpp v7, v57 row_ror:8 row_mask:0xf bank_mask:0xf
	v_cndmask_b32_e32 v118, v118, v4, vcc
	v_cndmask_b32_e32 v119, v119, v5, vcc
	v_cndmask_b32_e32 v120, v120, v6, vcc
	v_cndmask_b32_e32 v121, v121, v7, vcc
	v_cndmask_b32_e32 v54, v0, v54, vcc
	v_cndmask_b32_e32 v55, v1, v55, vcc
	v_cndmask_b32_e32 v56, v2, v56, vcc
	v_cndmask_b32_e32 v57, v3, v57, vcc
	ds_bpermute_b32 v118, v13, v118
	ds_bpermute_b32 v119, v13, v119
	ds_bpermute_b32 v120, v13, v120
	ds_bpermute_b32 v121, v13, v121
	ds_bpermute_b32 v54, v13, v54
	ds_bpermute_b32 v55, v13, v55
	ds_bpermute_b32 v56, v13, v56
	ds_bpermute_b32 v57, v13, v57
	s_waitcnt lgkmcnt(8)
	v_add_u32_e32 v10, 0x18000, v20
	global_store_dwordx4 v20, v[126:129], s[70:71]
	global_store_dwordx4 v10, v[62:65], s[70:71]
	v_cvt_pk_f16_f32 v122, v122, v123
	v_cvt_pk_f16_f32 v123, v124, v125
	v_cvt_pk_f16_f32 v124, v106, v107
	v_cvt_pk_f16_f32 v125, v108, v109
	v_cvt_pk_f16_f32 v58, v58, v59
	v_cvt_pk_f16_f32 v59, v60, v61
	v_cvt_pk_f16_f32 v60, v42, v43
	v_cvt_pk_f16_f32 v61, v44, v45
	v_mov_b32_dpp v0, v122 row_ror:8 row_mask:0xf bank_mask:0xf
	v_mov_b32_dpp v1, v123 row_ror:8 row_mask:0xf bank_mask:0xf
	v_mov_b32_dpp v2, v124 row_ror:8 row_mask:0xf bank_mask:0xf
	v_mov_b32_dpp v3, v125 row_ror:8 row_mask:0xf bank_mask:0xf
	v_mov_b32_dpp v4, v58 row_ror:8 row_mask:0xf bank_mask:0xf
	v_mov_b32_dpp v5, v59 row_ror:8 row_mask:0xf bank_mask:0xf
	v_mov_b32_dpp v6, v60 row_ror:8 row_mask:0xf bank_mask:0xf
	v_mov_b32_dpp v7, v61 row_ror:8 row_mask:0xf bank_mask:0xf
	v_cndmask_b32_e32 v122, v122, v4, vcc
	v_cndmask_b32_e32 v123, v123, v5, vcc
	v_cndmask_b32_e32 v124, v124, v6, vcc
	v_cndmask_b32_e32 v125, v125, v7, vcc
	v_cndmask_b32_e32 v58, v0, v58, vcc
	v_cndmask_b32_e32 v59, v1, v59, vcc
	v_cndmask_b32_e32 v60, v2, v60, vcc
	v_cndmask_b32_e32 v61, v3, v61, vcc
	ds_bpermute_b32 v122, v13, v122
	ds_bpermute_b32 v123, v13, v123
	ds_bpermute_b32 v124, v13, v124
	ds_bpermute_b32 v125, v13, v125
	ds_bpermute_b32 v58, v13, v58
	ds_bpermute_b32 v59, v13, v59
	ds_bpermute_b32 v60, v13, v60
	ds_bpermute_b32 v61, v13, v61
	s_waitcnt lgkmcnt(8)
	v_add_u32_e32 v10, 0x18000, v21
	global_store_dwordx4 v21, v[118:121], s[70:71]
	global_store_dwordx4 v10, v[54:57], s[70:71]
	v_cvt_pk_f16_f32 v114, v114, v115
	v_cvt_pk_f16_f32 v115, v116, v117
	v_cvt_pk_f16_f32 v116, v98, v99
	v_cvt_pk_f16_f32 v117, v100, v101
	v_cvt_pk_f16_f32 v50, v50, v51
	v_cvt_pk_f16_f32 v51, v52, v53
	v_cvt_pk_f16_f32 v52, v34, v35
	v_cvt_pk_f16_f32 v53, v36, v37
	v_mov_b32_dpp v0, v114 row_ror:8 row_mask:0xf bank_mask:0xf
	v_mov_b32_dpp v1, v115 row_ror:8 row_mask:0xf bank_mask:0xf
	v_mov_b32_dpp v2, v116 row_ror:8 row_mask:0xf bank_mask:0xf
	v_mov_b32_dpp v3, v117 row_ror:8 row_mask:0xf bank_mask:0xf
	v_mov_b32_dpp v4, v50 row_ror:8 row_mask:0xf bank_mask:0xf
	v_mov_b32_dpp v5, v51 row_ror:8 row_mask:0xf bank_mask:0xf
	v_mov_b32_dpp v6, v52 row_ror:8 row_mask:0xf bank_mask:0xf
	v_mov_b32_dpp v7, v53 row_ror:8 row_mask:0xf bank_mask:0xf
	v_cndmask_b32_e32 v114, v114, v4, vcc
	v_cndmask_b32_e32 v115, v115, v5, vcc
	v_cndmask_b32_e32 v116, v116, v6, vcc
	v_cndmask_b32_e32 v117, v117, v7, vcc
	v_cndmask_b32_e32 v50, v0, v50, vcc
	v_cndmask_b32_e32 v51, v1, v51, vcc
	v_cndmask_b32_e32 v52, v2, v52, vcc
	v_cndmask_b32_e32 v53, v3, v53, vcc
	ds_bpermute_b32 v114, v13, v114
	ds_bpermute_b32 v115, v13, v115
	ds_bpermute_b32 v116, v13, v116
	ds_bpermute_b32 v117, v13, v117
	ds_bpermute_b32 v50, v13, v50
	ds_bpermute_b32 v51, v13, v51
	ds_bpermute_b32 v52, v13, v52
	ds_bpermute_b32 v53, v13, v53
	s_waitcnt lgkmcnt(8)
	v_add_u32_e32 v10, 0x18000, v22
	global_store_dwordx4 v22, v[122:125], s[70:71]
	global_store_dwordx4 v10, v[58:61], s[70:71]
	s_waitcnt lgkmcnt(0)
	v_add_u32_e32 v10, 0x18000, v23
	global_store_dwordx4 v23, v[114:117], s[70:71]
	global_store_dwordx4 v10, v[50:53], s[70:71]
	s_mov_b64 s[4:5], 0
